# EpiResidNorm FINAL instance part 1: residual rows of units 1-7 prefetched four units ahead into a rotating register set with counted waits (was one vmcnt(0) round trip per unit)
# baseline (speedup 1.0000x reference)
; __device__ __forceinline__ float shx(float v, int m, int lane) { return __int_as_float(__builtin_amdgcn_ds_bpermute((lane ^ m) << 2, __float_as_int(v))); }
;     __device__ __forceinline__ void operator()(const f32x4 (&acc)[2][2][4][2], const Unit& u, int wr, int wc, int fr, int fq) const {
;     ...
;             for (int n = 0; n < 2; ++n) gv[bj][n] = *(const f32x4*)(gate + b * 9216 + col0 + bj * HALF + 4 * n) * coef;
;         h16x8 ov[2][4][2];
; #pragma unroll
;         for (int ai = 0; ai < 2; ++ai)
; #pragma unroll
;             for (int m = 0; m < 4; ++m) {
;                 float sq = 0.f;
; #pragma unroll
;                 for (int bj = 0; bj < 2; ++bj) {
;                     const unsigned off = (unsigned)(row0 + ai * HALF + m * 16) * DM + col0 + bj * HALF;
;                     f32x4 xa, xb;
;                     if (F32IN) { xa = *(const f32x4*)(in32 + off); xb = *(const f32x4*)(in32 + off + 4); }
;                     else { const h16x8 xv = *(const h16x8*)(in16 + off); xa = (f32x4){(float)xv[0], (float)xv[1], (float)xv[2], (float)xv[3]}; xb = (f32x4){(float)xv[4], (float)xv[5], (float)xv[6], (float)xv[7]}; }
;                     h16x8 o;
; #pragma unroll
;                     for (int j = 0; j < 4; ++j) { o[j] = (h16)(xa[j] + gv[bj][0][j] * acc[ai][bj][m][0][j]); o[4 + j] = (h16)(xb[j] + gv[bj][1][j] * acc[ai][bj][m][1][j]); }
;                     if (!FINAL) *(h16x8*)(out + off) = o;
;                     ov[ai][m][bj] = o;
; #pragma unroll
;                     for (int j = 0; j < 8; ++j) sq += (float)o[j] * (float)o[j];
;                 }
;                 sq += shx(sq, 16, lane); sq += shx(sq, 32, lane);
;                 if (fq == 0) red[(ai * HALF + wr * 64 + m * 16 + fr) * 4 + wc] = sq;
.LBB0_702:
	s_lshl_b32 s20, s24, 8
	v_or_b32_e32 v146, s20, v173
	v_lshl_add_u32 v144, s73, 18, v176
	v_readlane_b32 s22, v255, 27
	v_add_u32_e32 v32, v144, v146
	v_readlane_b32 s23, v255, 28
	s_lshr_b32 s18, s73, 4
	s_mulk_i32 s18, 0x2400
	v_lshl_add_u64 v[148:149], v[32:33], 1, s[22:23]
	global_load_dwordx4 v[148:151], v[148:149], off
	s_ashr_i32 s19, s18, 31
	s_lshl_b64 s[18:19], s[18:19], 2
	v_mov_b32_e32 v153, v33
	v_or_b32_e32 v152, 0x80, v32
	s_add_u32 s18, s35, s18
	v_lshl_add_u64 v[152:153], v[152:153], 1, s[22:23]
	v_ashrrev_i32_e32 v147, 31, v146
	s_addc_u32 s19, s54, s19
	global_load_dwordx4 v[152:155], v[152:153], off
	v_lshl_add_u64 v[160:161], v[146:147], 2, s[18:19]
	global_load_dwordx4 v[156:159], v[160:161], off
	global_load_dwordx4 v[164:167], v[160:161], off offset:16
	global_load_dwordx4 v[168:171], v[160:161], off offset:512
	global_load_dwordx4 v[204:207], v[160:161], off offset:528
	v_readlane_b32 s60, v255, 27
	v_readlane_b32 s61, v255, 28
	v_lshlrev_b32_e32 v251, 1, v32
	s_nop 3
	v_add_u32_e32 v250, 0x8000, v251
	global_load_dwordx4 v[226:229], v250, s[60:61]
	global_load_dwordx4 v[230:233], v250, s[60:61] offset:256
	v_add_u32_e32 v250, 0x10000, v251
	global_load_dwordx4 v[234:237], v250, s[60:61]
	global_load_dwordx4 v[238:241], v250, s[60:61] offset:256
	v_add_u32_e32 v250, 0x18000, v251
	global_load_dwordx4 v[242:245], v250, s[60:61]
	global_load_dwordx4 v[246:249], v250, s[60:61] offset:256
	v_add_u32_e32 v250, 0x40000, v251
	global_load_dwordx4 v[218:221], v250, s[60:61]
	global_load_dwordx4 v[222:225], v250, s[60:61] offset:256
	s_waitcnt vmcnt(8) lgkmcnt(0)
	v_cvt_f32_f16_e32 v190, v148
	v_cvt_f32_f16_sdwa v191, v148 dst_sel:DWORD dst_unused:UNUSED_PAD src0_sel:WORD_1
	v_cvt_f32_f16_e32 v196, v149
	v_cvt_f32_f16_sdwa v197, v149 dst_sel:DWORD dst_unused:UNUSED_PAD src0_sel:WORD_1
	v_cvt_f32_f16_e32 v198, v150
	v_cvt_f32_f16_sdwa v199, v150 dst_sel:DWORD dst_unused:UNUSED_PAD src0_sel:WORD_1
	v_cvt_f32_f16_e32 v208, v151
	v_cvt_f32_f16_sdwa v209, v151 dst_sel:DWORD dst_unused:UNUSED_PAD src0_sel:WORD_1
	v_pk_mul_f32 v[162:163], v[156:157], 0.5 op_sel_hi:[1,0]
	v_pk_mul_f32 v[160:161], v[158:159], 0.5 op_sel_hi:[1,0]
	v_pk_mul_f32 v[158:159], v[164:165], 0.5 op_sel_hi:[1,0]
	v_pk_fma_f32 v[126:127], v[126:127], v[162:163], v[190:191]
	v_cvt_f32_f16_e32 v210, v152
	v_cvt_f32_f16_sdwa v211, v152 dst_sel:DWORD dst_unused:UNUSED_PAD src0_sel:WORD_1
	v_cvt_f32_f16_e32 v212, v153
	v_cvt_f32_f16_sdwa v213, v153 dst_sel:DWORD dst_unused:UNUSED_PAD src0_sel:WORD_1
	v_cvt_f32_f16_e32 v216, v155
	v_cvt_f32_f16_sdwa v217, v155 dst_sel:DWORD dst_unused:UNUSED_PAD src0_sel:WORD_1
	v_pk_mul_f32 v[156:157], v[166:167], 0.5 op_sel_hi:[1,0]
	v_pk_fma_f32 v[128:129], v[128:129], v[160:161], v[196:197]
	v_pk_fma_f32 v[122:123], v[122:123], v[158:159], v[198:199]
	v_cvt_pk_f16_f32 v126, v126, v127
	v_pk_fma_f32 v[124:125], v[124:125], v[156:157], v[208:209]
	v_cvt_pk_f16_f32 v127, v128, v129
	v_cvt_pk_f16_f32 v128, v122, v123
	v_cvt_f32_f16_e32 v122, v126
	v_cvt_f32_f16_sdwa v123, v126 dst_sel:DWORD dst_unused:UNUSED_PAD src0_sel:WORD_1
	v_cvt_pk_f16_f32 v129, v124, v125
	v_cvt_f32_f16_e32 v124, v127
	v_cvt_f32_f16_sdwa v125, v127 dst_sel:DWORD dst_unused:UNUSED_PAD src0_sel:WORD_1
	v_cvt_f32_f16_e32 v214, v154
	v_cvt_f32_f16_sdwa v215, v154 dst_sel:DWORD dst_unused:UNUSED_PAD src0_sel:WORD_1
	v_pk_mul_f32 v[152:153], v[170:171], 0.5 op_sel_hi:[1,0]
	v_pk_mul_f32 v[154:155], v[168:169], 0.5 op_sel_hi:[1,0]
	v_pk_mul_f32 v[148:149], v[206:207], 0.5 op_sel_hi:[1,0]
	v_pk_fma_f32 v[118:119], v[118:119], v[154:155], v[210:211]
	v_pk_fma_f32 v[120:121], v[120:121], v[152:153], v[212:213]
	v_pk_fma_f32 v[116:117], v[116:117], v[148:149], v[216:217]
	v_cvt_f32_f16_e32 v126, v128
	v_cvt_f32_f16_sdwa v127, v128 dst_sel:DWORD dst_unused:UNUSED_PAD src0_sel:WORD_1
	v_cvt_pk_f16_f32 v118, v118, v119
	v_cvt_pk_f16_f32 v119, v120, v121
	v_cvt_pk_f16_f32 v145, v116, v117
	v_pk_mul_f32 v[164:165], v[122:123], v[122:123]
	v_cvt_f32_f16_e32 v128, v129
	v_cvt_f32_f16_sdwa v129, v129 dst_sel:DWORD dst_unused:UNUSED_PAD src0_sel:WORD_1
	v_cvt_f32_f16_e32 v116, v118
	v_cvt_f32_f16_sdwa v117, v118 dst_sel:DWORD dst_unused:UNUSED_PAD src0_sel:WORD_1
	v_cvt_f32_f16_e32 v120, v119
	v_cvt_f32_f16_sdwa v121, v119 dst_sel:DWORD dst_unused:UNUSED_PAD src0_sel:WORD_1
	v_cvt_f32_f16_e32 v118, v145
	v_cvt_f32_f16_sdwa v119, v145 dst_sel:DWORD dst_unused:UNUSED_PAD src0_sel:WORD_1
	v_pk_mul_f32 v[166:167], v[124:125], v[124:125]
	v_add_f32_e32 v145, v164, v165
	v_add_f32_e32 v145, v166, v145
	v_pk_mul_f32 v[168:169], v[126:127], v[126:127]
	v_add_f32_e32 v145, v167, v145
	v_pk_mul_f32 v[150:151], v[204:205], 0.5 op_sel_hi:[1,0]
	v_add_f32_e32 v145, v168, v145
	v_pk_fma_f32 v[114:115], v[114:115], v[150:151], v[214:215]
	v_pk_mul_f32 v[170:171], v[128:129], v[128:129]
	v_add_f32_e32 v145, v169, v145
	v_cvt_pk_f16_f32 v115, v114, v115
	v_add_f32_e32 v145, v170, v145
	v_cvt_f32_f16_e32 v114, v115
	v_cvt_f32_f16_sdwa v115, v115 dst_sel:DWORD dst_unused:UNUSED_PAD src0_sel:WORD_1
	v_pk_mul_f32 v[190:191], v[116:117], v[116:117]
	v_add_f32_e32 v145, v171, v145
	v_add_f32_e32 v145, v190, v145
	v_pk_mul_f32 v[196:197], v[120:121], v[120:121]
	v_add_f32_e32 v145, v191, v145
	v_add_f32_e32 v145, v196, v145
	v_pk_mul_f32 v[198:199], v[114:115], v[114:115]
	v_add_f32_e32 v145, v197, v145
	v_add_f32_e32 v145, v198, v145
	v_pk_mul_f32 v[204:205], v[118:119], v[118:119]
	v_add_f32_e32 v145, v199, v145
	v_add_f32_e32 v145, v204, v145
	v_add_f32_e32 v145, v205, v145
	ds_bpermute_b32 v164, v174, v145
	s_waitcnt lgkmcnt(0)
	v_add_f32_e32 v145, v145, v164
	ds_bpermute_b32 v164, v175, v145
	s_and_saveexec_b64 s[18:19], s[4:5]
	s_cbranch_execz .LBB0_704
	s_waitcnt lgkmcnt(0)
	v_add_f32_e32 v145, v145, v164
	ds_write_b32 v181, v145
; __device__ __forceinline__ float shx(float v, int m, int lane) { return __int_as_float(__builtin_amdgcn_ds_bpermute((lane ^ m) << 2, __float_as_int(v))); }
;     __device__ __forceinline__ void operator()(const f32x4 (&acc)[2][2][4][2], const Unit& u, int wr, int wc, int fr, int fq) const {
;     ...
;         for (int ai = 0; ai < 2; ++ai)
; #pragma unroll
;             for (int m = 0; m < 4; ++m) {
;                 float sq = 0.f;
; #pragma unroll
;                 for (int bj = 0; bj < 2; ++bj) {
;                     const unsigned off = (unsigned)(row0 + ai * HALF + m * 16) * DM + col0 + bj * HALF;
;                     f32x4 xa, xb;
;                     if (F32IN) { xa = *(const f32x4*)(in32 + off); xb = *(const f32x4*)(in32 + off + 4); }
;                     else { const h16x8 xv = *(const h16x8*)(in16 + off); xa = (f32x4){(float)xv[0], (float)xv[1], (float)xv[2], (float)xv[3]}; xb = (f32x4){(float)xv[4], (float)xv[5], (float)xv[6], (float)xv[7]}; }
;                     h16x8 o;
; #pragma unroll
;                     for (int j = 0; j < 4; ++j) { o[j] = (h16)(xa[j] + gv[bj][0][j] * acc[ai][bj][m][0][j]); o[4 + j] = (h16)(xb[j] + gv[bj][1][j] * acc[ai][bj][m][1][j]); }
;                     if (!FINAL) *(h16x8*)(out + off) = o;
;                     ov[ai][m][bj] = o;
; #pragma unroll
;                     for (int j = 0; j < 8; ++j) sq += (float)o[j] * (float)o[j];
;                 }
;                 sq += shx(sq, 16, lane); sq += shx(sq, 32, lane);
;                 if (fq == 0) red[(ai * HALF + wr * 64 + m * 16 + fr) * 4 + wc] = sq;
.LBB0_704:
	s_or_b64 exec, exec, s[18:19]
	v_readlane_b32 s18, v255, 27
	s_waitcnt lgkmcnt(0)
	v_add_u32_e32 v164, 0x4000, v32
	v_mov_b32_e32 v165, v33
	v_readlane_b32 s19, v255, 28
	v_add_u32_e32 v168, 0x4080, v32
	v_mov_b32_e32 v169, v33
	v_lshl_add_u64 v[164:165], v[164:165], 1, s[18:19]
	s_waitcnt vmcnt(6) lgkmcnt(0)
	v_mov_b64_e32 v[164:165], v[226:227]
	v_mov_b64_e32 v[166:167], v[228:229]
	v_mov_b64_e32 v[168:169], v[230:231]
	v_mov_b64_e32 v[170:171], v[232:233]
	v_add_u32_e32 v250, 0x48000, v251
	global_load_dwordx4 v[226:229], v250, s[60:61]
	global_load_dwordx4 v[230:233], v250, s[60:61] offset:256
	v_cvt_f32_f16_e32 v190, v164
	v_cvt_f32_f16_sdwa v191, v164 dst_sel:DWORD dst_unused:UNUSED_PAD src0_sel:WORD_1
	v_cvt_f32_f16_e32 v164, v165
	v_cvt_f32_f16_sdwa v165, v165 dst_sel:DWORD dst_unused:UNUSED_PAD src0_sel:WORD_1
	v_cvt_f32_f16_e32 v196, v166
	v_cvt_f32_f16_sdwa v197, v166 dst_sel:DWORD dst_unused:UNUSED_PAD src0_sel:WORD_1
	v_cvt_f32_f16_e32 v166, v167
	v_cvt_f32_f16_sdwa v167, v167 dst_sel:DWORD dst_unused:UNUSED_PAD src0_sel:WORD_1
	v_pk_fma_f32 v[110:111], v[110:111], v[162:163], v[190:191]
	v_pk_fma_f32 v[112:113], v[112:113], v[160:161], v[164:165]
	v_pk_fma_f32 v[106:107], v[106:107], v[158:159], v[196:197]
	v_cvt_pk_f16_f32 v110, v110, v111
	v_pk_fma_f32 v[108:109], v[108:109], v[156:157], v[166:167]
	v_cvt_pk_f16_f32 v111, v112, v113
	v_cvt_pk_f16_f32 v112, v106, v107
	v_cvt_f32_f16_e32 v106, v110
	v_cvt_f32_f16_sdwa v107, v110 dst_sel:DWORD dst_unused:UNUSED_PAD src0_sel:WORD_1
	v_cvt_f32_f16_e32 v198, v168
	v_cvt_f32_f16_sdwa v199, v168 dst_sel:DWORD dst_unused:UNUSED_PAD src0_sel:WORD_1
	v_cvt_pk_f16_f32 v113, v108, v109
	v_cvt_f32_f16_e32 v108, v111
	v_cvt_f32_f16_sdwa v109, v111 dst_sel:DWORD dst_unused:UNUSED_PAD src0_sel:WORD_1
	v_cvt_f32_f16_e32 v168, v169
	v_cvt_f32_f16_sdwa v169, v169 dst_sel:DWORD dst_unused:UNUSED_PAD src0_sel:WORD_1
	v_cvt_f32_f16_e32 v204, v170
	v_cvt_f32_f16_sdwa v205, v170 dst_sel:DWORD dst_unused:UNUSED_PAD src0_sel:WORD_1
	v_cvt_f32_f16_e32 v110, v112
	v_cvt_f32_f16_sdwa v111, v112 dst_sel:DWORD dst_unused:UNUSED_PAD src0_sel:WORD_1
	v_pk_mul_f32 v[164:165], v[106:107], v[106:107]
	v_cvt_f32_f16_e32 v170, v171
	v_cvt_f32_f16_sdwa v171, v171 dst_sel:DWORD dst_unused:UNUSED_PAD src0_sel:WORD_1
	v_pk_fma_f32 v[102:103], v[102:103], v[154:155], v[198:199]
	v_cvt_f32_f16_e32 v112, v113
	v_cvt_f32_f16_sdwa v113, v113 dst_sel:DWORD dst_unused:UNUSED_PAD src0_sel:WORD_1
	v_pk_mul_f32 v[166:167], v[108:109], v[108:109]
	v_add_f32_e32 v145, v164, v165
	v_pk_fma_f32 v[104:105], v[104:105], v[152:153], v[168:169]
	v_pk_fma_f32 v[98:99], v[98:99], v[150:151], v[204:205]
	v_cvt_pk_f16_f32 v102, v102, v103
	v_add_f32_e32 v145, v166, v145
	v_cvt_pk_f16_f32 v103, v104, v105
	v_cvt_pk_f16_f32 v104, v98, v99
	v_cvt_f32_f16_e32 v98, v102
	v_cvt_f32_f16_sdwa v99, v102 dst_sel:DWORD dst_unused:UNUSED_PAD src0_sel:WORD_1
	v_pk_mul_f32 v[168:169], v[110:111], v[110:111]
	v_add_f32_e32 v145, v167, v145
	v_add_f32_e32 v145, v168, v145
	v_pk_fma_f32 v[100:101], v[100:101], v[148:149], v[170:171]
	v_cvt_f32_f16_e32 v102, v103
	v_cvt_f32_f16_sdwa v103, v103 dst_sel:DWORD dst_unused:UNUSED_PAD src0_sel:WORD_1
	v_pk_mul_f32 v[170:171], v[112:113], v[112:113]
	v_add_f32_e32 v145, v169, v145
	v_add_f32_e32 v145, v170, v145
	v_cvt_pk_f16_f32 v105, v100, v101
	v_cvt_f32_f16_e32 v100, v104
	v_cvt_f32_f16_sdwa v101, v104 dst_sel:DWORD dst_unused:UNUSED_PAD src0_sel:WORD_1
	v_pk_mul_f32 v[190:191], v[98:99], v[98:99]
	v_add_f32_e32 v145, v171, v145
	v_add_f32_e32 v145, v190, v145
	v_cvt_f32_f16_e32 v104, v105
	v_cvt_f32_f16_sdwa v105, v105 dst_sel:DWORD dst_unused:UNUSED_PAD src0_sel:WORD_1
	v_pk_mul_f32 v[196:197], v[102:103], v[102:103]
	v_add_f32_e32 v145, v191, v145
	v_add_f32_e32 v145, v196, v145
	v_pk_mul_f32 v[198:199], v[100:101], v[100:101]
	v_add_f32_e32 v145, v197, v145
	v_add_f32_e32 v145, v198, v145
	v_pk_mul_f32 v[204:205], v[104:105], v[104:105]
	v_add_f32_e32 v145, v199, v145
	v_add_f32_e32 v145, v204, v145
	v_add_f32_e32 v145, v205, v145
	ds_bpermute_b32 v164, v174, v145
	s_waitcnt lgkmcnt(0)
	v_add_f32_e32 v145, v145, v164
	ds_bpermute_b32 v164, v175, v145
	s_and_saveexec_b64 s[18:19], s[4:5]
	s_cbranch_execz .LBB0_706
	s_waitcnt lgkmcnt(0)
	v_add_f32_e32 v145, v145, v164
	ds_write_b32 v181, v145 offset:256
; __device__ __forceinline__ float shx(float v, int m, int lane) { return __int_as_float(__builtin_amdgcn_ds_bpermute((lane ^ m) << 2, __float_as_int(v))); }
;     __device__ __forceinline__ void operator()(const f32x4 (&acc)[2][2][4][2], const Unit& u, int wr, int wc, int fr, int fq) const {
;     ...
;         for (int ai = 0; ai < 2; ++ai)
; #pragma unroll
;             for (int m = 0; m < 4; ++m) {
;                 float sq = 0.f;
; #pragma unroll
;                 for (int bj = 0; bj < 2; ++bj) {
;                     const unsigned off = (unsigned)(row0 + ai * HALF + m * 16) * DM + col0 + bj * HALF;
;                     f32x4 xa, xb;
;                     if (F32IN) { xa = *(const f32x4*)(in32 + off); xb = *(const f32x4*)(in32 + off + 4); }
;                     else { const h16x8 xv = *(const h16x8*)(in16 + off); xa = (f32x4){(float)xv[0], (float)xv[1], (float)xv[2], (float)xv[3]}; xb = (f32x4){(float)xv[4], (float)xv[5], (float)xv[6], (float)xv[7]}; }
;                     h16x8 o;
; #pragma unroll
;                     for (int j = 0; j < 4; ++j) { o[j] = (h16)(xa[j] + gv[bj][0][j] * acc[ai][bj][m][0][j]); o[4 + j] = (h16)(xb[j] + gv[bj][1][j] * acc[ai][bj][m][1][j]); }
;                     if (!FINAL) *(h16x8*)(out + off) = o;
;                     ov[ai][m][bj] = o;
; #pragma unroll
;                     for (int j = 0; j < 8; ++j) sq += (float)o[j] * (float)o[j];
;                 }
;                 sq += shx(sq, 16, lane); sq += shx(sq, 32, lane);
;                 if (fq == 0) red[(ai * HALF + wr * 64 + m * 16 + fr) * 4 + wc] = sq;
.LBB0_706:
	s_or_b64 exec, exec, s[18:19]
	v_readlane_b32 s18, v255, 27
	s_waitcnt lgkmcnt(0)
	v_add_u32_e32 v164, 0x8000, v32
	v_mov_b32_e32 v165, v33
	v_readlane_b32 s19, v255, 28
	v_add_u32_e32 v168, 0x8080, v32
	v_mov_b32_e32 v169, v33
	v_lshl_add_u64 v[164:165], v[164:165], 1, s[18:19]
	s_waitcnt vmcnt(6) lgkmcnt(0)
	v_mov_b64_e32 v[164:165], v[234:235]
	v_mov_b64_e32 v[166:167], v[236:237]
	v_mov_b64_e32 v[168:169], v[238:239]
	v_mov_b64_e32 v[170:171], v[240:241]
	v_add_u32_e32 v250, 0x50000, v251
	global_load_dwordx4 v[234:237], v250, s[60:61]
	global_load_dwordx4 v[238:241], v250, s[60:61] offset:256
	v_cvt_f32_f16_e32 v190, v164
	v_cvt_f32_f16_sdwa v191, v164 dst_sel:DWORD dst_unused:UNUSED_PAD src0_sel:WORD_1
	v_cvt_f32_f16_e32 v164, v165
	v_cvt_f32_f16_sdwa v165, v165 dst_sel:DWORD dst_unused:UNUSED_PAD src0_sel:WORD_1
	v_cvt_f32_f16_e32 v196, v166
	v_cvt_f32_f16_sdwa v197, v166 dst_sel:DWORD dst_unused:UNUSED_PAD src0_sel:WORD_1
	v_cvt_f32_f16_e32 v166, v167
	v_cvt_f32_f16_sdwa v167, v167 dst_sel:DWORD dst_unused:UNUSED_PAD src0_sel:WORD_1
	v_pk_fma_f32 v[94:95], v[94:95], v[162:163], v[190:191]
	v_cvt_f32_f16_e32 v198, v168
	v_cvt_f32_f16_sdwa v199, v168 dst_sel:DWORD dst_unused:UNUSED_PAD src0_sel:WORD_1
	v_cvt_f32_f16_e32 v168, v169
	v_cvt_f32_f16_sdwa v169, v169 dst_sel:DWORD dst_unused:UNUSED_PAD src0_sel:WORD_1
	v_cvt_f32_f16_e32 v204, v170
	v_cvt_f32_f16_sdwa v205, v170 dst_sel:DWORD dst_unused:UNUSED_PAD src0_sel:WORD_1
	v_cvt_f32_f16_e32 v170, v171
	v_cvt_f32_f16_sdwa v171, v171 dst_sel:DWORD dst_unused:UNUSED_PAD src0_sel:WORD_1
	v_pk_fma_f32 v[96:97], v[96:97], v[160:161], v[164:165]
	v_pk_fma_f32 v[90:91], v[90:91], v[158:159], v[196:197]
	v_cvt_pk_f16_f32 v94, v94, v95
	v_pk_fma_f32 v[92:93], v[92:93], v[156:157], v[166:167]
	v_cvt_pk_f16_f32 v95, v96, v97
	v_cvt_pk_f16_f32 v96, v90, v91
	v_cvt_f32_f16_e32 v90, v94
	v_cvt_f32_f16_sdwa v91, v94 dst_sel:DWORD dst_unused:UNUSED_PAD src0_sel:WORD_1
	v_cvt_pk_f16_f32 v97, v92, v93
	v_cvt_f32_f16_e32 v92, v95
	v_cvt_f32_f16_sdwa v93, v95 dst_sel:DWORD dst_unused:UNUSED_PAD src0_sel:WORD_1
	v_pk_fma_f32 v[86:87], v[86:87], v[154:155], v[198:199]
	v_pk_fma_f32 v[88:89], v[88:89], v[152:153], v[168:169]
	v_pk_fma_f32 v[84:85], v[84:85], v[148:149], v[170:171]
	v_cvt_f32_f16_e32 v94, v96
	v_cvt_f32_f16_sdwa v95, v96 dst_sel:DWORD dst_unused:UNUSED_PAD src0_sel:WORD_1
	v_cvt_pk_f16_f32 v86, v86, v87
	v_cvt_pk_f16_f32 v87, v88, v89
	v_cvt_pk_f16_f32 v145, v84, v85
	v_pk_mul_f32 v[164:165], v[90:91], v[90:91]
	v_cvt_f32_f16_e32 v96, v97
	v_cvt_f32_f16_sdwa v97, v97 dst_sel:DWORD dst_unused:UNUSED_PAD src0_sel:WORD_1
	v_cvt_f32_f16_e32 v84, v86
	v_cvt_f32_f16_sdwa v85, v86 dst_sel:DWORD dst_unused:UNUSED_PAD src0_sel:WORD_1
	v_cvt_f32_f16_e32 v88, v87
	v_cvt_f32_f16_sdwa v89, v87 dst_sel:DWORD dst_unused:UNUSED_PAD src0_sel:WORD_1
	v_cvt_f32_f16_e32 v86, v145
	v_cvt_f32_f16_sdwa v87, v145 dst_sel:DWORD dst_unused:UNUSED_PAD src0_sel:WORD_1
	v_pk_mul_f32 v[166:167], v[92:93], v[92:93]
	v_add_f32_e32 v145, v164, v165
	v_add_f32_e32 v145, v166, v145
	v_pk_mul_f32 v[168:169], v[94:95], v[94:95]
	v_add_f32_e32 v145, v167, v145
	v_add_f32_e32 v145, v168, v145
	v_pk_fma_f32 v[82:83], v[82:83], v[150:151], v[204:205]
	v_pk_mul_f32 v[170:171], v[96:97], v[96:97]
	v_add_f32_e32 v145, v169, v145
	v_cvt_pk_f16_f32 v83, v82, v83
	v_add_f32_e32 v145, v170, v145
	v_cvt_f32_f16_e32 v82, v83
	v_cvt_f32_f16_sdwa v83, v83 dst_sel:DWORD dst_unused:UNUSED_PAD src0_sel:WORD_1
	v_pk_mul_f32 v[190:191], v[84:85], v[84:85]
	v_add_f32_e32 v145, v171, v145
	v_add_f32_e32 v145, v190, v145
	v_pk_mul_f32 v[196:197], v[88:89], v[88:89]
	v_add_f32_e32 v145, v191, v145
	v_add_f32_e32 v145, v196, v145
	v_pk_mul_f32 v[198:199], v[82:83], v[82:83]
	v_add_f32_e32 v145, v197, v145
	v_add_f32_e32 v145, v198, v145
	v_pk_mul_f32 v[204:205], v[86:87], v[86:87]
	v_add_f32_e32 v145, v199, v145
	v_add_f32_e32 v145, v204, v145
	v_add_f32_e32 v145, v205, v145
	ds_bpermute_b32 v164, v174, v145
	s_waitcnt lgkmcnt(0)
	v_add_f32_e32 v145, v145, v164
	ds_bpermute_b32 v164, v175, v145
	s_and_saveexec_b64 s[18:19], s[4:5]
	s_cbranch_execz .LBB0_708
	s_waitcnt lgkmcnt(0)
	v_add_f32_e32 v145, v145, v164
	ds_write_b32 v181, v145 offset:512
.LBB0_708:
	s_or_b64 exec, exec, s[18:19]
	v_readlane_b32 s18, v255, 27
	s_waitcnt lgkmcnt(0)
	v_add_u32_e32 v164, 0xc000, v32
	v_mov_b32_e32 v165, v33
	v_readlane_b32 s19, v255, 28
	v_add_u32_e32 v168, 0xc080, v32
	v_mov_b32_e32 v169, v33
	v_lshl_add_u64 v[164:165], v[164:165], 1, s[18:19]
	s_waitcnt vmcnt(6) lgkmcnt(0)
; __device__ __forceinline__ float shx(float v, int m, int lane) { return __int_as_float(__builtin_amdgcn_ds_bpermute((lane ^ m) << 2, __float_as_int(v))); }
;     __device__ __forceinline__ void operator()(const f32x4 (&acc)[2][2][4][2], const Unit& u, int wr, int wc, int fr, int fq) const {
;     ...
;         for (int ai = 0; ai < 2; ++ai)
; #pragma unroll
;             for (int m = 0; m < 4; ++m) {
;                 float sq = 0.f;
; #pragma unroll
;                 for (int bj = 0; bj < 2; ++bj) {
;                     const unsigned off = (unsigned)(row0 + ai * HALF + m * 16) * DM + col0 + bj * HALF;
;                     f32x4 xa, xb;
;                     if (F32IN) { xa = *(const f32x4*)(in32 + off); xb = *(const f32x4*)(in32 + off + 4); }
;                     else { const h16x8 xv = *(const h16x8*)(in16 + off); xa = (f32x4){(float)xv[0], (float)xv[1], (float)xv[2], (float)xv[3]}; xb = (f32x4){(float)xv[4], (float)xv[5], (float)xv[6], (float)xv[7]}; }
;                     h16x8 o;
; #pragma unroll
;                     for (int j = 0; j < 4; ++j) { o[j] = (h16)(xa[j] + gv[bj][0][j] * acc[ai][bj][m][0][j]); o[4 + j] = (h16)(xb[j] + gv[bj][1][j] * acc[ai][bj][m][1][j]); }
;                     if (!FINAL) *(h16x8*)(out + off) = o;
;                     ov[ai][m][bj] = o;
; #pragma unroll
;                     for (int j = 0; j < 8; ++j) sq += (float)o[j] * (float)o[j];
;                 }
;                 sq += shx(sq, 16, lane); sq += shx(sq, 32, lane);
;                 if (fq == 0) red[(ai * HALF + wr * 64 + m * 16 + fr) * 4 + wc] = sq;
	v_mov_b64_e32 v[164:165], v[242:243]
	v_mov_b64_e32 v[166:167], v[244:245]
	v_mov_b64_e32 v[168:169], v[246:247]
	v_mov_b64_e32 v[170:171], v[248:249]
	v_add_u32_e32 v250, 0x58000, v251
	global_load_dwordx4 v[242:245], v250, s[60:61]
	v_cvt_f32_f16_e32 v190, v164
	v_cvt_f32_f16_sdwa v191, v164 dst_sel:DWORD dst_unused:UNUSED_PAD src0_sel:WORD_1
	v_cvt_f32_f16_e32 v164, v165
	v_cvt_f32_f16_sdwa v165, v165 dst_sel:DWORD dst_unused:UNUSED_PAD src0_sel:WORD_1
	v_cvt_f32_f16_e32 v196, v166
	v_cvt_f32_f16_sdwa v197, v166 dst_sel:DWORD dst_unused:UNUSED_PAD src0_sel:WORD_1
	v_cvt_f32_f16_e32 v166, v167
	v_cvt_f32_f16_sdwa v167, v167 dst_sel:DWORD dst_unused:UNUSED_PAD src0_sel:WORD_1
	v_pk_fma_f32 v[78:79], v[78:79], v[162:163], v[190:191]
	v_pk_fma_f32 v[80:81], v[80:81], v[160:161], v[164:165]
	v_pk_fma_f32 v[74:75], v[74:75], v[158:159], v[196:197]
	v_cvt_pk_f16_f32 v78, v78, v79
	v_pk_fma_f32 v[76:77], v[76:77], v[156:157], v[166:167]
	v_cvt_pk_f16_f32 v79, v80, v81
	v_cvt_pk_f16_f32 v80, v74, v75
	v_cvt_f32_f16_e32 v74, v78
	v_cvt_f32_f16_sdwa v75, v78 dst_sel:DWORD dst_unused:UNUSED_PAD src0_sel:WORD_1
	v_cvt_f32_f16_e32 v198, v168
	v_cvt_f32_f16_sdwa v199, v168 dst_sel:DWORD dst_unused:UNUSED_PAD src0_sel:WORD_1
	v_cvt_pk_f16_f32 v81, v76, v77
	v_cvt_f32_f16_e32 v76, v79
	v_cvt_f32_f16_sdwa v77, v79 dst_sel:DWORD dst_unused:UNUSED_PAD src0_sel:WORD_1
	v_cvt_f32_f16_e32 v168, v169
	v_cvt_f32_f16_sdwa v169, v169 dst_sel:DWORD dst_unused:UNUSED_PAD src0_sel:WORD_1
	v_cvt_f32_f16_e32 v204, v170
	v_cvt_f32_f16_sdwa v205, v170 dst_sel:DWORD dst_unused:UNUSED_PAD src0_sel:WORD_1
	v_cvt_f32_f16_e32 v78, v80
	v_cvt_f32_f16_sdwa v79, v80 dst_sel:DWORD dst_unused:UNUSED_PAD src0_sel:WORD_1
	v_pk_mul_f32 v[164:165], v[74:75], v[74:75]
	v_cvt_f32_f16_e32 v170, v171
	v_cvt_f32_f16_sdwa v171, v171 dst_sel:DWORD dst_unused:UNUSED_PAD src0_sel:WORD_1
	v_pk_fma_f32 v[70:71], v[70:71], v[154:155], v[198:199]
	v_cvt_f32_f16_e32 v80, v81
	v_cvt_f32_f16_sdwa v81, v81 dst_sel:DWORD dst_unused:UNUSED_PAD src0_sel:WORD_1
	v_pk_mul_f32 v[166:167], v[76:77], v[76:77]
	v_add_f32_e32 v145, v164, v165
	v_pk_fma_f32 v[72:73], v[72:73], v[152:153], v[168:169]
	v_pk_fma_f32 v[66:67], v[66:67], v[150:151], v[204:205]
	v_cvt_pk_f16_f32 v70, v70, v71
	v_add_f32_e32 v145, v166, v145
	v_cvt_pk_f16_f32 v71, v72, v73
	v_cvt_pk_f16_f32 v72, v66, v67
	v_cvt_f32_f16_e32 v66, v70
	v_cvt_f32_f16_sdwa v67, v70 dst_sel:DWORD dst_unused:UNUSED_PAD src0_sel:WORD_1
	v_pk_mul_f32 v[168:169], v[78:79], v[78:79]
	v_add_f32_e32 v145, v167, v145
	v_add_f32_e32 v145, v168, v145
	v_pk_fma_f32 v[68:69], v[68:69], v[148:149], v[170:171]
	v_cvt_f32_f16_e32 v70, v71
	v_cvt_f32_f16_sdwa v71, v71 dst_sel:DWORD dst_unused:UNUSED_PAD src0_sel:WORD_1
	v_pk_mul_f32 v[170:171], v[80:81], v[80:81]
	v_add_f32_e32 v145, v169, v145
	v_add_f32_e32 v145, v170, v145
	v_cvt_pk_f16_f32 v73, v68, v69
	v_cvt_f32_f16_e32 v68, v72
	v_cvt_f32_f16_sdwa v69, v72 dst_sel:DWORD dst_unused:UNUSED_PAD src0_sel:WORD_1
	v_pk_mul_f32 v[190:191], v[66:67], v[66:67]
	v_add_f32_e32 v145, v171, v145
	v_add_f32_e32 v145, v190, v145
	v_cvt_f32_f16_e32 v72, v73
	v_cvt_f32_f16_sdwa v73, v73 dst_sel:DWORD dst_unused:UNUSED_PAD src0_sel:WORD_1
	v_pk_mul_f32 v[196:197], v[70:71], v[70:71]
	v_add_f32_e32 v145, v191, v145
	v_add_f32_e32 v145, v196, v145
	v_pk_mul_f32 v[198:199], v[68:69], v[68:69]
	v_add_f32_e32 v145, v197, v145
	v_add_f32_e32 v145, v198, v145
	v_pk_mul_f32 v[204:205], v[72:73], v[72:73]
	v_add_f32_e32 v145, v199, v145
	v_add_f32_e32 v145, v204, v145
	v_add_f32_e32 v145, v205, v145
	ds_bpermute_b32 v164, v174, v145
	s_waitcnt lgkmcnt(0)
	v_add_f32_e32 v145, v145, v164
	ds_bpermute_b32 v164, v175, v145
	s_and_saveexec_b64 s[18:19], s[4:5]
	s_cbranch_execz .LBB0_710
	s_waitcnt lgkmcnt(0)
	v_add_f32_e32 v145, v145, v164
	ds_write_b32 v181, v145 offset:768
.LBB0_710:
	s_or_b64 exec, exec, s[18:19]
	v_readlane_b32 s18, v255, 27
	s_waitcnt lgkmcnt(0)
	v_add_u32_e32 v164, 0x20000, v32
	v_mov_b32_e32 v165, v33
	v_readlane_b32 s19, v255, 28
	v_add_u32_e32 v168, 0x20080, v32
	v_mov_b32_e32 v169, v33
	v_lshl_add_u64 v[164:165], v[164:165], 1, s[18:19]
	s_waitcnt vmcnt(5) lgkmcnt(0)
	v_mov_b64_e32 v[164:165], v[218:219]
	v_mov_b64_e32 v[166:167], v[220:221]
	v_mov_b64_e32 v[168:169], v[222:223]
	v_mov_b64_e32 v[170:171], v[224:225]
	v_cvt_f32_f16_e32 v190, v164
	v_cvt_f32_f16_sdwa v191, v164 dst_sel:DWORD dst_unused:UNUSED_PAD src0_sel:WORD_1
	v_cvt_f32_f16_e32 v164, v165
	v_cvt_f32_f16_sdwa v165, v165 dst_sel:DWORD dst_unused:UNUSED_PAD src0_sel:WORD_1
	v_cvt_f32_f16_e32 v196, v166
	v_cvt_f32_f16_sdwa v197, v166 dst_sel:DWORD dst_unused:UNUSED_PAD src0_sel:WORD_1
	v_cvt_f32_f16_e32 v166, v167
	v_cvt_f32_f16_sdwa v167, v167 dst_sel:DWORD dst_unused:UNUSED_PAD src0_sel:WORD_1
	v_pk_fma_f32 v[62:63], v[62:63], v[162:163], v[190:191]
	v_cvt_f32_f16_e32 v198, v168
	v_cvt_f32_f16_sdwa v199, v168 dst_sel:DWORD dst_unused:UNUSED_PAD src0_sel:WORD_1
	v_cvt_f32_f16_e32 v168, v169
	v_cvt_f32_f16_sdwa v169, v169 dst_sel:DWORD dst_unused:UNUSED_PAD src0_sel:WORD_1
	v_cvt_f32_f16_e32 v204, v170
	v_cvt_f32_f16_sdwa v205, v170 dst_sel:DWORD dst_unused:UNUSED_PAD src0_sel:WORD_1
	v_cvt_f32_f16_e32 v170, v171
	v_cvt_f32_f16_sdwa v171, v171 dst_sel:DWORD dst_unused:UNUSED_PAD src0_sel:WORD_1
	v_pk_fma_f32 v[64:65], v[64:65], v[160:161], v[164:165]
	v_pk_fma_f32 v[58:59], v[58:59], v[158:159], v[196:197]
	v_cvt_pk_f16_f32 v62, v62, v63
	v_pk_fma_f32 v[60:61], v[60:61], v[156:157], v[166:167]
	v_cvt_pk_f16_f32 v63, v64, v65
	v_cvt_pk_f16_f32 v64, v58, v59
	v_cvt_f32_f16_e32 v58, v62
	v_cvt_f32_f16_sdwa v59, v62 dst_sel:DWORD dst_unused:UNUSED_PAD src0_sel:WORD_1
; __device__ __forceinline__ float shx(float v, int m, int lane) { return __int_as_float(__builtin_amdgcn_ds_bpermute((lane ^ m) << 2, __float_as_int(v))); }
;     __device__ __forceinline__ void operator()(const f32x4 (&acc)[2][2][4][2], const Unit& u, int wr, int wc, int fr, int fq) const {
;     ...
;         for (int ai = 0; ai < 2; ++ai)
; #pragma unroll
;             for (int m = 0; m < 4; ++m) {
;                 float sq = 0.f;
; #pragma unroll
;                 for (int bj = 0; bj < 2; ++bj) {
;                     const unsigned off = (unsigned)(row0 + ai * HALF + m * 16) * DM + col0 + bj * HALF;
;                     f32x4 xa, xb;
;                     if (F32IN) { xa = *(const f32x4*)(in32 + off); xb = *(const f32x4*)(in32 + off + 4); }
;                     else { const h16x8 xv = *(const h16x8*)(in16 + off); xa = (f32x4){(float)xv[0], (float)xv[1], (float)xv[2], (float)xv[3]}; xb = (f32x4){(float)xv[4], (float)xv[5], (float)xv[6], (float)xv[7]}; }
;                     h16x8 o;
; #pragma unroll
;                     for (int j = 0; j < 4; ++j) { o[j] = (h16)(xa[j] + gv[bj][0][j] * acc[ai][bj][m][0][j]); o[4 + j] = (h16)(xb[j] + gv[bj][1][j] * acc[ai][bj][m][1][j]); }
;                     if (!FINAL) *(h16x8*)(out + off) = o;
;                     ov[ai][m][bj] = o;
; #pragma unroll
;                     for (int j = 0; j < 8; ++j) sq += (float)o[j] * (float)o[j];
;                 }
;                 sq += shx(sq, 16, lane); sq += shx(sq, 32, lane);
;                 if (fq == 0) red[(ai * HALF + wr * 64 + m * 16 + fr) * 4 + wc] = sq;
	v_cvt_pk_f16_f32 v65, v60, v61
	v_cvt_f32_f16_e32 v60, v63
	v_cvt_f32_f16_sdwa v61, v63 dst_sel:DWORD dst_unused:UNUSED_PAD src0_sel:WORD_1
	v_pk_fma_f32 v[54:55], v[54:55], v[154:155], v[198:199]
	v_pk_fma_f32 v[56:57], v[56:57], v[152:153], v[168:169]
	v_pk_fma_f32 v[52:53], v[52:53], v[148:149], v[170:171]
	v_cvt_f32_f16_e32 v62, v64
	v_cvt_f32_f16_sdwa v63, v64 dst_sel:DWORD dst_unused:UNUSED_PAD src0_sel:WORD_1
	v_cvt_pk_f16_f32 v54, v54, v55
	v_cvt_pk_f16_f32 v55, v56, v57
	v_cvt_pk_f16_f32 v145, v52, v53
	v_pk_mul_f32 v[164:165], v[58:59], v[58:59]
	v_cvt_f32_f16_e32 v64, v65
	v_cvt_f32_f16_sdwa v65, v65 dst_sel:DWORD dst_unused:UNUSED_PAD src0_sel:WORD_1
	v_cvt_f32_f16_e32 v52, v54
	v_cvt_f32_f16_sdwa v53, v54 dst_sel:DWORD dst_unused:UNUSED_PAD src0_sel:WORD_1
	v_cvt_f32_f16_e32 v56, v55
	v_cvt_f32_f16_sdwa v57, v55 dst_sel:DWORD dst_unused:UNUSED_PAD src0_sel:WORD_1
	v_cvt_f32_f16_e32 v54, v145
	v_cvt_f32_f16_sdwa v55, v145 dst_sel:DWORD dst_unused:UNUSED_PAD src0_sel:WORD_1
	v_pk_mul_f32 v[166:167], v[60:61], v[60:61]
	v_add_f32_e32 v145, v164, v165
	v_add_f32_e32 v145, v166, v145
	v_pk_mul_f32 v[168:169], v[62:63], v[62:63]
	v_add_f32_e32 v145, v167, v145
	v_add_f32_e32 v145, v168, v145
	v_pk_fma_f32 v[50:51], v[50:51], v[150:151], v[204:205]
	v_pk_mul_f32 v[170:171], v[64:65], v[64:65]
	v_add_f32_e32 v145, v169, v145
	v_cvt_pk_f16_f32 v51, v50, v51
	v_add_f32_e32 v145, v170, v145
	v_cvt_f32_f16_e32 v50, v51
	v_cvt_f32_f16_sdwa v51, v51 dst_sel:DWORD dst_unused:UNUSED_PAD src0_sel:WORD_1
	v_pk_mul_f32 v[190:191], v[52:53], v[52:53]
	v_add_f32_e32 v145, v171, v145
	v_add_f32_e32 v145, v190, v145
	v_pk_mul_f32 v[196:197], v[56:57], v[56:57]
	v_add_f32_e32 v145, v191, v145
	v_add_f32_e32 v145, v196, v145
	v_pk_mul_f32 v[198:199], v[50:51], v[50:51]
	v_add_f32_e32 v145, v197, v145
	v_add_f32_e32 v145, v198, v145
	v_pk_mul_f32 v[204:205], v[54:55], v[54:55]
	v_add_f32_e32 v145, v199, v145
	v_add_f32_e32 v145, v204, v145
	v_add_f32_e32 v145, v205, v145
	ds_bpermute_b32 v164, v174, v145
	s_waitcnt lgkmcnt(0)
	v_add_f32_e32 v145, v145, v164
	ds_bpermute_b32 v164, v175, v145
	s_and_saveexec_b64 s[18:19], s[4:5]
	s_cbranch_execz .LBB0_712
	s_waitcnt lgkmcnt(0)
	v_add_f32_e32 v145, v145, v164
	ds_write_b32 v181, v145 offset:2048
.LBB0_712:
	s_or_b64 exec, exec, s[18:19]
	v_readlane_b32 s18, v255, 27
	s_waitcnt lgkmcnt(0)
	v_add_u32_e32 v164, 0x24000, v32
	v_mov_b32_e32 v165, v33
	v_readlane_b32 s19, v255, 28
	v_add_u32_e32 v168, 0x24080, v32
	v_mov_b32_e32 v169, v33
	v_lshl_add_u64 v[164:165], v[164:165], 1, s[18:19]
	s_waitcnt vmcnt(3) lgkmcnt(0)
	v_mov_b64_e32 v[164:165], v[226:227]
	v_mov_b64_e32 v[166:167], v[228:229]
	v_mov_b64_e32 v[168:169], v[230:231]
	v_mov_b64_e32 v[170:171], v[232:233]
	v_cvt_f32_f16_e32 v190, v164
	v_cvt_f32_f16_sdwa v191, v164 dst_sel:DWORD dst_unused:UNUSED_PAD src0_sel:WORD_1
	v_cvt_f32_f16_e32 v164, v165
	v_cvt_f32_f16_sdwa v165, v165 dst_sel:DWORD dst_unused:UNUSED_PAD src0_sel:WORD_1
	v_cvt_f32_f16_e32 v196, v166
	v_cvt_f32_f16_sdwa v197, v166 dst_sel:DWORD dst_unused:UNUSED_PAD src0_sel:WORD_1
	v_cvt_f32_f16_e32 v166, v167
	v_cvt_f32_f16_sdwa v167, v167 dst_sel:DWORD dst_unused:UNUSED_PAD src0_sel:WORD_1
	v_cvt_f32_f16_e32 v198, v168
	v_cvt_f32_f16_sdwa v199, v168 dst_sel:DWORD dst_unused:UNUSED_PAD src0_sel:WORD_1
	v_cvt_f32_f16_e32 v168, v169
	v_cvt_f32_f16_sdwa v169, v169 dst_sel:DWORD dst_unused:UNUSED_PAD src0_sel:WORD_1
	v_cvt_f32_f16_e32 v204, v170
	v_cvt_f32_f16_sdwa v205, v170 dst_sel:DWORD dst_unused:UNUSED_PAD src0_sel:WORD_1
	v_cvt_f32_f16_e32 v170, v171
	v_cvt_f32_f16_sdwa v171, v171 dst_sel:DWORD dst_unused:UNUSED_PAD src0_sel:WORD_1
	v_pk_fma_f32 v[46:47], v[46:47], v[162:163], v[190:191]
	v_pk_fma_f32 v[48:49], v[48:49], v[160:161], v[164:165]
	v_pk_fma_f32 v[44:45], v[44:45], v[156:157], v[166:167]
	v_cvt_pk_f16_f32 v46, v46, v47
	v_cvt_pk_f16_f32 v47, v48, v49
	v_cvt_pk_f16_f32 v145, v44, v45
	v_cvt_f32_f16_e32 v44, v46
	v_cvt_f32_f16_sdwa v45, v46 dst_sel:DWORD dst_unused:UNUSED_PAD src0_sel:WORD_1
	v_pk_fma_f32 v[42:43], v[42:43], v[158:159], v[196:197]
	v_cvt_f32_f16_e32 v48, v47
	v_cvt_f32_f16_sdwa v49, v47 dst_sel:DWORD dst_unused:UNUSED_PAD src0_sel:WORD_1
	v_pk_fma_f32 v[38:39], v[38:39], v[154:155], v[198:199]
	v_pk_fma_f32 v[40:41], v[40:41], v[152:153], v[168:169]
	v_pk_fma_f32 v[36:37], v[36:37], v[148:149], v[170:171]
	v_cvt_pk_f16_f32 v43, v42, v43
	v_cvt_pk_f16_f32 v38, v38, v39
	v_cvt_pk_f16_f32 v39, v40, v41
	v_cvt_pk_f16_f32 v164, v36, v37
	v_cvt_f32_f16_e32 v42, v43
	v_cvt_f32_f16_sdwa v43, v43 dst_sel:DWORD dst_unused:UNUSED_PAD src0_sel:WORD_1
	v_cvt_f32_f16_e32 v36, v38
	v_cvt_f32_f16_sdwa v37, v38 dst_sel:DWORD dst_unused:UNUSED_PAD src0_sel:WORD_1
	v_cvt_f32_f16_e32 v40, v39
	v_cvt_f32_f16_sdwa v41, v39 dst_sel:DWORD dst_unused:UNUSED_PAD src0_sel:WORD_1
	v_cvt_f32_f16_e32 v38, v164
	v_cvt_f32_f16_sdwa v39, v164 dst_sel:DWORD dst_unused:UNUSED_PAD src0_sel:WORD_1
	v_pk_mul_f32 v[164:165], v[44:45], v[44:45]
	v_cvt_f32_f16_e32 v46, v145
	v_cvt_f32_f16_sdwa v47, v145 dst_sel:DWORD dst_unused:UNUSED_PAD src0_sel:WORD_1
	v_pk_mul_f32 v[166:167], v[48:49], v[48:49]
	v_add_f32_e32 v145, v164, v165
	v_add_f32_e32 v145, v166, v145
	v_pk_mul_f32 v[168:169], v[42:43], v[42:43]
	v_add_f32_e32 v145, v167, v145
	v_add_f32_e32 v145, v168, v145
	v_pk_fma_f32 v[34:35], v[34:35], v[150:151], v[204:205]
	v_pk_mul_f32 v[170:171], v[46:47], v[46:47]
	v_add_f32_e32 v145, v169, v145
	v_cvt_pk_f16_f32 v35, v34, v35
	v_add_f32_e32 v145, v170, v145
	v_cvt_f32_f16_e32 v34, v35
	v_cvt_f32_f16_sdwa v35, v35 dst_sel:DWORD dst_unused:UNUSED_PAD src0_sel:WORD_1
	v_pk_mul_f32 v[190:191], v[36:37], v[36:37]
	v_add_f32_e32 v145, v171, v145
	v_add_f32_e32 v145, v190, v145
	v_pk_mul_f32 v[196:197], v[40:41], v[40:41]
	v_add_f32_e32 v145, v191, v145
	v_add_f32_e32 v145, v196, v145
	v_pk_mul_f32 v[198:199], v[34:35], v[34:35]
	v_add_f32_e32 v145, v197, v145
	v_add_f32_e32 v145, v198, v145
	v_pk_mul_f32 v[204:205], v[38:39], v[38:39]
	v_add_f32_e32 v145, v199, v145
	v_add_f32_e32 v145, v204, v145
	v_add_f32_e32 v145, v205, v145
	ds_bpermute_b32 v164, v174, v145
	s_waitcnt lgkmcnt(0)
	v_add_f32_e32 v145, v145, v164
	ds_bpermute_b32 v164, v175, v145
	s_and_saveexec_b64 s[18:19], s[4:5]
	s_cbranch_execz .LBB0_714
	s_waitcnt lgkmcnt(0)
	v_add_f32_e32 v145, v145, v164
	ds_write_b32 v181, v145 offset:2304
; __device__ __forceinline__ float shx(float v, int m, int lane) { return __int_as_float(__builtin_amdgcn_ds_bpermute((lane ^ m) << 2, __float_as_int(v))); }
;     __device__ __forceinline__ void operator()(const f32x4 (&acc)[2][2][4][2], const Unit& u, int wr, int wc, int fr, int fq) const {
;     ...
;         for (int ai = 0; ai < 2; ++ai)
; #pragma unroll
;             for (int m = 0; m < 4; ++m) {
;                 float sq = 0.f;
; #pragma unroll
;                 for (int bj = 0; bj < 2; ++bj) {
;                     const unsigned off = (unsigned)(row0 + ai * HALF + m * 16) * DM + col0 + bj * HALF;
;                     f32x4 xa, xb;
;                     if (F32IN) { xa = *(const f32x4*)(in32 + off); xb = *(const f32x4*)(in32 + off + 4); }
;                     else { const h16x8 xv = *(const h16x8*)(in16 + off); xa = (f32x4){(float)xv[0], (float)xv[1], (float)xv[2], (float)xv[3]}; xb = (f32x4){(float)xv[4], (float)xv[5], (float)xv[6], (float)xv[7]}; }
;                     h16x8 o;
; #pragma unroll
;                     for (int j = 0; j < 4; ++j) { o[j] = (h16)(xa[j] + gv[bj][0][j] * acc[ai][bj][m][0][j]); o[4 + j] = (h16)(xb[j] + gv[bj][1][j] * acc[ai][bj][m][1][j]); }
;                     if (!FINAL) *(h16x8*)(out + off) = o;
;                     ov[ai][m][bj] = o;
; #pragma unroll
;                     for (int j = 0; j < 8; ++j) sq += (float)o[j] * (float)o[j];
;                 }
;                 sq += shx(sq, 16, lane); sq += shx(sq, 32, lane);
;                 if (fq == 0) red[(ai * HALF + wr * 64 + m * 16 + fr) * 4 + wc] = sq;
.LBB0_714:
	s_or_b64 exec, exec, s[18:19]
	v_readlane_b32 s18, v255, 27
	s_waitcnt lgkmcnt(0)
	v_add_u32_e32 v164, 0x28000, v32
	v_mov_b32_e32 v165, v33
	v_readlane_b32 s19, v255, 28
	v_add_u32_e32 v168, 0x28080, v32
	v_mov_b32_e32 v169, v33
	v_lshl_add_u64 v[164:165], v[164:165], 1, s[18:19]
	s_waitcnt vmcnt(1) lgkmcnt(0)
	v_mov_b64_e32 v[164:165], v[234:235]
	v_mov_b64_e32 v[166:167], v[236:237]
	v_mov_b64_e32 v[168:169], v[238:239]
	v_mov_b64_e32 v[170:171], v[240:241]
	v_cvt_f32_f16_e32 v190, v164
	v_cvt_f32_f16_sdwa v191, v164 dst_sel:DWORD dst_unused:UNUSED_PAD src0_sel:WORD_1
	v_cvt_f32_f16_e32 v164, v165
	v_cvt_f32_f16_sdwa v165, v165 dst_sel:DWORD dst_unused:UNUSED_PAD src0_sel:WORD_1
	v_cvt_f32_f16_e32 v196, v166
	v_cvt_f32_f16_sdwa v197, v166 dst_sel:DWORD dst_unused:UNUSED_PAD src0_sel:WORD_1
	v_cvt_f32_f16_e32 v166, v167
	v_cvt_f32_f16_sdwa v167, v167 dst_sel:DWORD dst_unused:UNUSED_PAD src0_sel:WORD_1
	v_cvt_f32_f16_e32 v198, v168
	v_cvt_f32_f16_sdwa v199, v168 dst_sel:DWORD dst_unused:UNUSED_PAD src0_sel:WORD_1
	v_cvt_f32_f16_e32 v168, v169
	v_cvt_f32_f16_sdwa v169, v169 dst_sel:DWORD dst_unused:UNUSED_PAD src0_sel:WORD_1
	v_cvt_f32_f16_e32 v204, v170
	v_cvt_f32_f16_sdwa v205, v170 dst_sel:DWORD dst_unused:UNUSED_PAD src0_sel:WORD_1
	v_cvt_f32_f16_e32 v170, v171
	v_cvt_f32_f16_sdwa v171, v171 dst_sel:DWORD dst_unused:UNUSED_PAD src0_sel:WORD_1
	v_pk_fma_f32 v[28:29], v[28:29], v[162:163], v[190:191]
	v_pk_fma_f32 v[30:31], v[30:31], v[160:161], v[164:165]
	v_pk_fma_f32 v[26:27], v[26:27], v[156:157], v[166:167]
	v_cvt_pk_f16_f32 v28, v28, v29
	v_cvt_pk_f16_f32 v29, v30, v31
	v_cvt_pk_f16_f32 v145, v26, v27
	v_cvt_f32_f16_e32 v26, v28
	v_cvt_f32_f16_sdwa v27, v28 dst_sel:DWORD dst_unused:UNUSED_PAD src0_sel:WORD_1
	v_pk_fma_f32 v[24:25], v[24:25], v[158:159], v[196:197]
	v_cvt_f32_f16_e32 v30, v29
	v_cvt_f32_f16_sdwa v31, v29 dst_sel:DWORD dst_unused:UNUSED_PAD src0_sel:WORD_1
	v_pk_fma_f32 v[20:21], v[20:21], v[154:155], v[198:199]
	v_pk_fma_f32 v[22:23], v[22:23], v[152:153], v[168:169]
	v_pk_fma_f32 v[18:19], v[18:19], v[148:149], v[170:171]
	v_cvt_pk_f16_f32 v25, v24, v25
	v_cvt_pk_f16_f32 v20, v20, v21
	v_cvt_pk_f16_f32 v21, v22, v23
	v_cvt_pk_f16_f32 v164, v18, v19
	v_cvt_f32_f16_e32 v24, v25
	v_cvt_f32_f16_sdwa v25, v25 dst_sel:DWORD dst_unused:UNUSED_PAD src0_sel:WORD_1
	v_cvt_f32_f16_e32 v18, v20
	v_cvt_f32_f16_sdwa v19, v20 dst_sel:DWORD dst_unused:UNUSED_PAD src0_sel:WORD_1
	v_cvt_f32_f16_e32 v22, v21
	v_cvt_f32_f16_sdwa v23, v21 dst_sel:DWORD dst_unused:UNUSED_PAD src0_sel:WORD_1
	v_cvt_f32_f16_e32 v20, v164
	v_cvt_f32_f16_sdwa v21, v164 dst_sel:DWORD dst_unused:UNUSED_PAD src0_sel:WORD_1
	v_pk_mul_f32 v[164:165], v[26:27], v[26:27]
	v_cvt_f32_f16_e32 v28, v145
	v_cvt_f32_f16_sdwa v29, v145 dst_sel:DWORD dst_unused:UNUSED_PAD src0_sel:WORD_1
	v_pk_mul_f32 v[166:167], v[30:31], v[30:31]
	v_add_f32_e32 v145, v164, v165
	v_add_f32_e32 v145, v166, v145
	v_pk_mul_f32 v[168:169], v[24:25], v[24:25]
	v_add_f32_e32 v145, v167, v145
	v_add_f32_e32 v145, v168, v145
	v_pk_fma_f32 v[16:17], v[16:17], v[150:151], v[204:205]
	v_pk_mul_f32 v[170:171], v[28:29], v[28:29]
	v_add_f32_e32 v145, v169, v145
	v_cvt_pk_f16_f32 v17, v16, v17
	v_add_f32_e32 v145, v170, v145
	v_cvt_f32_f16_e32 v16, v17
	v_cvt_f32_f16_sdwa v17, v17 dst_sel:DWORD dst_unused:UNUSED_PAD src0_sel:WORD_1
	v_pk_mul_f32 v[190:191], v[18:19], v[18:19]
	v_add_f32_e32 v145, v171, v145
	v_add_f32_e32 v145, v190, v145
	v_pk_mul_f32 v[196:197], v[22:23], v[22:23]
	v_add_f32_e32 v145, v191, v145
	v_add_f32_e32 v145, v196, v145
	v_pk_mul_f32 v[198:199], v[16:17], v[16:17]
	v_add_f32_e32 v145, v197, v145
	v_add_f32_e32 v145, v198, v145
	v_pk_mul_f32 v[204:205], v[20:21], v[20:21]
	v_add_f32_e32 v145, v199, v145
	v_add_f32_e32 v145, v204, v145
	v_add_f32_e32 v145, v205, v145
	ds_bpermute_b32 v164, v174, v145
	s_waitcnt lgkmcnt(0)
	v_add_f32_e32 v145, v145, v164
	ds_bpermute_b32 v164, v175, v145
	s_and_saveexec_b64 s[18:19], s[4:5]
	s_cbranch_execz .LBB0_716
	s_waitcnt lgkmcnt(0)
	v_add_f32_e32 v145, v145, v164
	ds_write_b32 v181, v145 offset:2560
; __device__ __forceinline__ float shx(float v, int m, int lane) { return __int_as_float(__builtin_amdgcn_ds_bpermute((lane ^ m) << 2, __float_as_int(v))); }
;     __device__ __forceinline__ void operator()(const f32x4 (&acc)[2][2][4][2], const Unit& u, int wr, int wc, int fr, int fq) const {
;     ...
;         for (int ai = 0; ai < 2; ++ai)
; #pragma unroll
;             for (int m = 0; m < 4; ++m) {
;                 float sq = 0.f;
; #pragma unroll
;                 for (int bj = 0; bj < 2; ++bj) {
;                     const unsigned off = (unsigned)(row0 + ai * HALF + m * 16) * DM + col0 + bj * HALF;
;                     f32x4 xa, xb;
;                     if (F32IN) { xa = *(const f32x4*)(in32 + off); xb = *(const f32x4*)(in32 + off + 4); }
;                     else { const h16x8 xv = *(const h16x8*)(in16 + off); xa = (f32x4){(float)xv[0], (float)xv[1], (float)xv[2], (float)xv[3]}; xb = (f32x4){(float)xv[4], (float)xv[5], (float)xv[6], (float)xv[7]}; }
;                     h16x8 o;
; #pragma unroll
;                     for (int j = 0; j < 4; ++j) { o[j] = (h16)(xa[j] + gv[bj][0][j] * acc[ai][bj][m][0][j]); o[4 + j] = (h16)(xb[j] + gv[bj][1][j] * acc[ai][bj][m][1][j]); }
;                     if (!FINAL) *(h16x8*)(out + off) = o;
;                     ov[ai][m][bj] = o;
; #pragma unroll
;                     for (int j = 0; j < 8; ++j) sq += (float)o[j] * (float)o[j];
;                 }
;                 sq += shx(sq, 16, lane); sq += shx(sq, 32, lane);
;                 if (fq == 0) red[(ai * HALF + wr * 64 + m * 16 + fr) * 4 + wc] = sq;
.LBB0_716:
	s_or_b64 exec, exec, s[18:19]
	v_readlane_b32 s18, v255, 27
	s_waitcnt lgkmcnt(0)
	v_add_u32_e32 v164, 0x2c000, v32
	v_mov_b32_e32 v165, v33
	v_readlane_b32 s19, v255, 28
	v_add_u32_e32 v32, 0x2c080, v32
	s_nop 0
	v_lshl_add_u64 v[164:165], v[164:165], 1, s[18:19]
	s_waitcnt vmcnt(0) lgkmcnt(0)
	v_mov_b64_e32 v[164:165], v[242:243]
	v_mov_b64_e32 v[166:167], v[244:245]
	v_cvt_f32_f16_e32 v168, v164
	v_cvt_f32_f16_sdwa v169, v164 dst_sel:DWORD dst_unused:UNUSED_PAD src0_sel:WORD_1
	v_cvt_f32_f16_e32 v164, v165
	v_cvt_f32_f16_sdwa v165, v165 dst_sel:DWORD dst_unused:UNUSED_PAD src0_sel:WORD_1
	v_pk_fma_f32 v[12:13], v[12:13], v[162:163], v[168:169]
	s_nop 0
	v_cvt_pk_f16_f32 v13, v12, v13
	v_pk_fma_f32 v[14:15], v[14:15], v[160:161], v[164:165]
	v_cvt_f32_f16_e32 v164, v166
	v_cvt_f32_f16_sdwa v165, v166 dst_sel:DWORD dst_unused:UNUSED_PAD src0_sel:WORD_1
	v_cvt_f32_f16_e32 v12, v13
	v_cvt_f32_f16_sdwa v13, v13 dst_sel:DWORD dst_unused:UNUSED_PAD src0_sel:WORD_1
	v_cvt_pk_f16_f32 v15, v14, v15
	v_pk_fma_f32 v[8:9], v[8:9], v[158:159], v[164:165]
	v_cvt_f32_f16_e32 v14, v15
	v_cvt_pk_f16_f32 v8, v8, v9
	v_cvt_f32_f16_e32 v158, v8
	v_cvt_f32_f16_sdwa v159, v8 dst_sel:DWORD dst_unused:UNUSED_PAD src0_sel:WORD_1
	v_cvt_f32_f16_e32 v8, v167
	v_cvt_f32_f16_sdwa v9, v167 dst_sel:DWORD dst_unused:UNUSED_PAD src0_sel:WORD_1
	v_cvt_f32_f16_sdwa v15, v15 dst_sel:DWORD dst_unused:UNUSED_PAD src0_sel:WORD_1
	v_pk_mul_f32 v[162:163], v[12:13], v[12:13]
	v_pk_mul_f32 v[164:165], v[158:159], v[158:159]
	v_pk_fma_f32 v[8:9], v[10:11], v[156:157], v[8:9]
	v_pk_mul_f32 v[160:161], v[14:15], v[14:15]
	v_cvt_pk_f16_f32 v8, v8, v9
	v_cvt_f32_f16_e32 v10, v8
	v_cvt_f32_f16_sdwa v11, v8 dst_sel:DWORD dst_unused:UNUSED_PAD src0_sel:WORD_1
	v_lshl_add_u64 v[8:9], v[32:33], 1, s[18:19]
	global_load_dwordx4 v[166:169], v[8:9], off
	v_add_f32_e32 v32, v162, v163
	v_add_f32_e32 v32, v160, v32
	v_add_f32_e32 v32, v161, v32
	v_add_f32_e32 v32, v164, v32
	v_pk_mul_f32 v[156:157], v[10:11], v[10:11]
	v_add_f32_e32 v32, v165, v32
	v_add_f32_e32 v32, v156, v32
	v_add_f32_e32 v32, v157, v32
	s_waitcnt vmcnt(0) lgkmcnt(0)
	v_cvt_f32_f16_e32 v8, v166
	v_cvt_f32_f16_sdwa v9, v166 dst_sel:DWORD dst_unused:UNUSED_PAD src0_sel:WORD_1
	v_pk_fma_f32 v[4:5], v[4:5], v[154:155], v[8:9]
	v_cvt_f32_f16_e32 v154, v167
	v_cvt_f32_f16_sdwa v155, v167 dst_sel:DWORD dst_unused:UNUSED_PAD src0_sel:WORD_1
	v_cvt_pk_f16_f32 v4, v4, v5
	v_cvt_f32_f16_e32 v8, v4
	v_cvt_f32_f16_sdwa v9, v4 dst_sel:DWORD dst_unused:UNUSED_PAD src0_sel:WORD_1
	v_pk_fma_f32 v[6:7], v[6:7], v[152:153], v[154:155]
	v_cvt_f32_f16_e32 v154, v168
	v_cvt_f32_f16_sdwa v155, v168 dst_sel:DWORD dst_unused:UNUSED_PAD src0_sel:WORD_1
	v_cvt_pk_f16_f32 v6, v6, v7
	v_cvt_f32_f16_e32 v152, v6
	v_cvt_f32_f16_sdwa v153, v6 dst_sel:DWORD dst_unused:UNUSED_PAD src0_sel:WORD_1
	v_pk_fma_f32 v[0:1], v[0:1], v[150:151], v[154:155]
	v_cvt_f32_f16_e32 v154, v169
	v_cvt_f32_f16_sdwa v155, v169 dst_sel:DWORD dst_unused:UNUSED_PAD src0_sel:WORD_1
	v_cvt_pk_f16_f32 v0, v0, v1
	v_pk_mul_f32 v[4:5], v[8:9], v[8:9]
	v_cvt_f32_f16_e32 v150, v0
	v_cvt_f32_f16_sdwa v151, v0 dst_sel:DWORD dst_unused:UNUSED_PAD src0_sel:WORD_1
	v_pk_fma_f32 v[2:3], v[2:3], v[148:149], v[154:155]
	v_add_f32_e32 v4, v4, v32
	v_cvt_pk_f16_f32 v2, v2, v3
	v_pk_mul_f32 v[6:7], v[152:153], v[152:153]
	v_cvt_f32_f16_e32 v148, v2
	v_cvt_f32_f16_sdwa v149, v2 dst_sel:DWORD dst_unused:UNUSED_PAD src0_sel:WORD_1
	v_add_f32_e32 v4, v5, v4
	v_add_f32_e32 v4, v6, v4
	v_pk_mul_f32 v[0:1], v[150:151], v[150:151]
	v_add_f32_e32 v4, v7, v4
	v_add_f32_e32 v0, v0, v4
	v_pk_mul_f32 v[2:3], v[148:149], v[148:149]
	v_add_f32_e32 v0, v1, v0
	v_add_f32_e32 v0, v2, v0
	v_add_f32_e32 v0, v3, v0
	ds_bpermute_b32 v1, v174, v0
	s_waitcnt lgkmcnt(0)
	v_add_f32_e32 v0, v0, v1
	ds_bpermute_b32 v1, v175, v0
	s_and_saveexec_b64 s[18:19], s[4:5]
	s_cbranch_execz .LBB0_718
	s_waitcnt lgkmcnt(0)
	v_add_f32_e32 v0, v0, v1
	ds_write_b32 v181, v0 offset:2816
